# code placement: 60 bytes of s_nop after the attention phase so P7-P10 code keeps the baseline's 64-byte alignment (previous version shifted them by 4 mod 8 bytes)
# speedup vs baseline: 1.0019x; 1.0019x over previous
; __device__ __forceinline__ int tid_of(int wv) { int l; asm volatile("v_mbcnt_lo_u32_b32 %0, -1, 0\n\tv_mbcnt_hi_u32_b32 %0, -1, %0" : "=v"(l)); return wv * 64 + l; }
; __device__ __forceinline__ void xcd_barrier(const XcdBarrier& b, const int wv) {
;     asm volatile("s_waitcnt vmcnt(0)" ::: "memory");
;     __syncthreads();
;     if (tid_of(wv) == 0) {
;         unsigned* bar = b.bar;
;         __builtin_amdgcn_s_waitcnt(0);
;         unsigned nloc = b.st[0], nx = b.st[1];
;         if (nloc == 0u) { xcd_barrier_complete(bar, b.x, nloc, nx); b.st[0] = nloc; b.st[1] = nx; }
.LBB0_1200:
	s_nop 0
	s_nop 0
	s_nop 0
	s_nop 0
	s_nop 0
	s_nop 0
	s_nop 0
	s_nop 0
	s_nop 0
	s_nop 0
	s_nop 0
	s_nop 0
	s_nop 0
	s_nop 0
	s_nop 0
	s_waitcnt vmcnt(0)
	s_waitcnt lgkmcnt(0)
	s_barrier
	v_mbcnt_lo_u32_b32 v0, -1, 0
	v_mbcnt_hi_u32_b32 v0, -1, v0
	s_nop 0
	v_cmp_eq_u32_e32 vcc, s75, v0
	s_and_saveexec_b64 s[2:3], vcc
	s_cbranch_execz .LBB0_1252
	s_add_i32 s4, 0, 0x23fc0
	v_mov_b32_e32 v0, s4
	s_waitcnt vmcnt(0) expcnt(0) lgkmcnt(0)
	ds_read_b32 v2, v0
	s_add_i32 s4, 0, 0x23fc4
	v_mov_b32_e32 v0, s4
	ds_read_b32 v0, v0
	s_waitcnt lgkmcnt(1)
	v_cmp_ne_u32_e32 vcc, 0, v2
	s_cbranch_vccnz .LBB0_1216
	s_add_u32 s4, s10, 0x1000
	s_addc_u32 s5, s11, 0
	s_add_u32 s6, s10, 0x1100
	s_addc_u32 s7, s11, 0
	s_add_u32 s20, s10, 0x1200
	s_addc_u32 s21, s11, 0
	s_mul_i32 s29, s13, s9
	s_add_u32 s22, s10, 0x1300
	s_mul_i32 s29, s29, s12
	s_addc_u32 s23, s11, 0
	s_mov_b32 s31, 1
	v_mov_b32_e32 v16, 0
	s_branch .LBB0_1204
